# plus: filter-MLP hidden-layer jobs load all 33 / 64 weights of a step in one batch (one wait per layer)
# speedup vs baseline: 1.0088x; 1.0088x over previous
; __device__ __forceinline__ void p0_job(const Params& p, char* smem, int job) {
;     ...
;       float a = b1;
;       for (int i = 0; i < 33; ++i) a += zf[tg * 36 + i] * w1[i * 64 + j];
;       h1s[tg * 64 + j] = sinf(fr * a);
.LBB0_54:
	s_or_b64 exec, exec, s[26:27]
	s_waitcnt lgkmcnt(0)
	s_barrier
	ds_read_b128 v[0:3], v166
	ds_read_b128 v[174:177], v166 offset:16
	ds_read_b128 v[178:181], v166 offset:32
	ds_read_b128 v[182:185], v166 offset:48
	global_load_dword v186, v[10:11], off
	global_load_dword v187, v[12:13], off
	global_load_dword v188, v[10:11], off offset:256
	global_load_dword v189, v[10:11], off offset:512
	global_load_dword v190, v[10:11], off offset:768
	global_load_dword v191, v[10:11], off offset:1024
	global_load_dword v192, v[10:11], off offset:1280
	global_load_dword v193, v[10:11], off offset:1536
	global_load_dword v194, v[10:11], off offset:1792
	global_load_dword v195, v[10:11], off offset:2048
	global_load_dword v196, v[10:11], off offset:2304
	global_load_dword v197, v[10:11], off offset:2560
	global_load_dword v198, v[10:11], off offset:2816
	global_load_dword v199, v[10:11], off offset:3072
	global_load_dword v200, v[10:11], off offset:3328
	global_load_dword v201, v[10:11], off offset:3584
	global_load_dword v202, v[10:11], off offset:3840
	global_load_dword v204, v[14:15], off
	global_load_dword v205, v[16:17], off
	global_load_dword v206, v[18:19], off
	global_load_dword v207, v[20:21], off
	global_load_dword v208, v[22:23], off
	global_load_dword v209, v[24:25], off
	global_load_dword v210, v[26:27], off
	global_load_dword v211, v[28:29], off
	global_load_dword v212, v[30:31], off
	global_load_dword v213, v[32:33], off
	global_load_dword v214, v[34:35], off
	global_load_dword v215, v[36:37], off
	global_load_dword v216, v[38:39], off
	global_load_dword v217, v[40:41], off
	global_load_dword v218, v[42:43], off
	global_load_dword v219, v[44:45], off
	s_waitcnt vmcnt(0)
	s_waitcnt lgkmcnt(0)
	v_fma_f32 v4, v0, v186, v162
	v_fmac_f32_e32 v4, v1, v188
	v_fmac_f32_e32 v4, v2, v189
	v_fmac_f32_e32 v4, v3, v190
	v_fmac_f32_e32 v4, v174, v191
	v_fmac_f32_e32 v4, v175, v192
	v_fmac_f32_e32 v4, v176, v193
	v_fmac_f32_e32 v4, v177, v194
	v_fmac_f32_e32 v4, v178, v195
	v_fmac_f32_e32 v4, v179, v196
	v_fmac_f32_e32 v4, v180, v197
	v_fmac_f32_e32 v4, v181, v198
	v_fmac_f32_e32 v4, v182, v199
	v_fmac_f32_e32 v4, v183, v200
	v_fmac_f32_e32 v4, v184, v201
	v_fmac_f32_e32 v4, v185, v202
	ds_read_b128 v[0:3], v166 offset:64
	s_waitcnt lgkmcnt(0)
	v_fmac_f32_e32 v4, v0, v187
	v_fmac_f32_e32 v4, v1, v204
	v_fmac_f32_e32 v4, v2, v205
	v_fmac_f32_e32 v4, v3, v206
	ds_read_b96 v[0:2], v166 offset:80
	s_waitcnt lgkmcnt(0)
	v_fmac_f32_e32 v4, v0, v207
	v_fmac_f32_e32 v4, v1, v208
	v_fmac_f32_e32 v4, v2, v209
	ds_read2_b32 v[2:3], v166 offset0:23 offset1:24
	s_waitcnt lgkmcnt(0)
	v_pk_mul_f32 v[0:1], v[2:3], v[210:211]
	s_nop 0
	v_add_f32_e32 v0, v4, v0
	v_add_f32_e32 v4, v0, v1
	ds_read2_b32 v[2:3], v166 offset0:25 offset1:26
	s_waitcnt lgkmcnt(0)
	v_pk_mul_f32 v[0:1], v[2:3], v[212:213]
	s_nop 0
	v_add_f32_e32 v0, v4, v0
	v_add_f32_e32 v4, v0, v1
	ds_read2_b32 v[2:3], v166 offset0:27 offset1:28
	s_waitcnt lgkmcnt(0)
	v_pk_mul_f32 v[0:1], v[2:3], v[214:215]
	s_nop 0
	v_add_f32_e32 v0, v4, v0
	v_add_f32_e32 v4, v0, v1
	ds_read2_b32 v[2:3], v166 offset0:29 offset1:30
	s_waitcnt lgkmcnt(0)
	v_pk_mul_f32 v[0:1], v[2:3], v[216:217]
	s_nop 0
	v_add_f32_e32 v0, v4, v0
	v_add_f32_e32 v4, v0, v1
	ds_read2_b32 v[2:3], v166 offset0:31 offset1:32
	s_waitcnt lgkmcnt(0)
	v_pk_mul_f32 v[0:1], v[2:3], v[218:219]
	s_nop 0
	v_add_f32_e32 v0, v4, v0
	v_add_f32_e32 v0, v0, v1
	v_mul_f32_e32 v0, v164, v0
	v_and_b32_e32 v1, 0x7fffffff, v0
	v_cmp_nlt_f32_e64 s[0:1], |v0|, s47
	s_and_saveexec_b64 s[10:11], s[0:1]
	s_xor_b64 s[26:27], exec, s[10:11]
	s_cbranch_execz .LBB0_56
	v_lshrrev_b32_e32 v2, 23, v1
	v_add_u32_e32 v2, 0xffffff88, v2
	v_cmp_lt_u32_e32 vcc, 63, v2
	s_nop 1
	v_cndmask_b32_e32 v3, 0, v156, vcc
	v_add_u32_e32 v2, v3, v2
	v_cmp_lt_u32_e64 s[0:1], 31, v2
	s_nop 1
	v_cndmask_b32_e64 v3, 0, v157, s[0:1]
	v_add_u32_e32 v2, v3, v2
	v_cmp_lt_u32_e64 s[12:13], 31, v2
	s_nop 1
	v_cndmask_b32_e64 v3, 0, v157, s[12:13]
	v_add_u32_e32 v147, v3, v2
	v_and_b32_e32 v2, 0x7fffff, v1
	v_or_b32_e32 v173, 0x800000, v2
	v_mad_u64_u32 v[2:3], s[10:11], v173, s48, 0
	v_mov_b32_e32 v4, v3
	v_mad_u64_u32 v[170:171], s[10:11], v173, s49, v[4:5]
	v_mov_b32_e32 v4, v171
	v_mad_u64_u32 v[174:175], s[10:11], v173, s50, v[4:5]
	v_mov_b32_e32 v4, v175
	v_mad_u64_u32 v[176:177], s[10:11], v173, s51, v[4:5]
	v_mov_b32_e32 v4, v177
	v_mad_u64_u32 v[178:179], s[10:11], v173, s52, v[4:5]
	v_mov_b32_e32 v4, v179
	v_mad_u64_u32 v[180:181], s[10:11], v173, s53, v[4:5]
	v_mov_b32_e32 v4, v181
	v_mad_u64_u32 v[182:183], s[10:11], v173, s54, v[4:5]
	v_cndmask_b32_e32 v3, v180, v176, vcc
	v_cndmask_b32_e32 v4, v182, v178, vcc
	v_cndmask_b32_e32 v173, v183, v180, vcc
	v_cndmask_b32_e64 v171, v4, v3, s[0:1]
	v_cndmask_b32_e64 v4, v173, v4, s[0:1]
	v_cndmask_b32_e32 v173, v178, v174, vcc
	v_cndmask_b32_e64 v3, v3, v173, s[0:1]
	v_sub_u32_e32 v175, 32, v147
	v_cmp_eq_u32_e64 s[14:15], 0, v147
	v_cndmask_b32_e32 v147, v176, v170, vcc
	v_cndmask_b32_e64 v4, v4, v171, s[12:13]
	v_cndmask_b32_e64 v171, v171, v3, s[12:13]
	v_cndmask_b32_e64 v170, v173, v147, s[0:1]
	v_alignbit_b32 v177, v4, v171, v175
	v_cndmask_b32_e64 v3, v3, v170, s[12:13]
	v_cndmask_b32_e64 v4, v177, v4, s[14:15]
	v_alignbit_b32 v173, v171, v3, v175
	v_cndmask_b32_e32 v2, v174, v2, vcc
	v_cndmask_b32_e64 v171, v173, v171, s[14:15]
	v_bfe_u32 v177, v4, 29, 1
	v_cndmask_b32_e64 v2, v147, v2, s[0:1]
	v_alignbit_b32 v173, v4, v171, 30
	v_sub_u32_e32 v178, 0, v177
	v_cndmask_b32_e64 v2, v170, v2, s[12:13]
	v_xor_b32_e32 v173, v173, v178
	v_alignbit_b32 v147, v3, v2, v175
	v_cndmask_b32_e64 v3, v147, v3, s[14:15]
	v_ffbh_u32_e32 v170, v173
	v_alignbit_b32 v147, v171, v3, 30
	v_min_u32_e32 v170, 32, v170
	v_alignbit_b32 v2, v3, v2, 30
	v_xor_b32_e32 v147, v147, v178
	v_sub_u32_e32 v171, 31, v170
	v_xor_b32_e32 v2, v2, v178
	v_alignbit_b32 v173, v173, v147, v171
	v_alignbit_b32 v2, v147, v2, v171
	v_alignbit_b32 v3, v173, v2, 9
	v_ffbh_u32_e32 v147, v3
	v_min_u32_e32 v147, 32, v147
	v_lshrrev_b32_e32 v176, 29, v4
	v_not_b32_e32 v171, v147
	v_alignbit_b32 v2, v3, v2, v171
	v_lshlrev_b32_e32 v3, 31, v176
	v_or_b32_e32 v171, 0x33000000, v3
	v_add_lshl_u32 v147, v147, v170, 23
	v_lshrrev_b32_e32 v2, 9, v2
	v_sub_u32_e32 v147, v171, v147
	v_or_b32_e32 v3, 0.5, v3
	v_lshlrev_b32_e32 v170, 23, v170
	v_or_b32_e32 v2, v147, v2
	v_lshrrev_b32_e32 v147, 9, v173
	v_sub_u32_e32 v3, v3, v170
	v_or_b32_e32 v3, v147, v3
	v_mul_f32_e32 v147, 0x3fc90fda, v3
	v_fma_f32 v170, v3, s55, -v147
	v_fmac_f32_e32 v170, 0x33a22168, v3
	v_fmac_f32_e32 v170, 0x3fc90fda, v2
	v_lshrrev_b32_e32 v2, 30, v4
	v_add_f32_e32 v3, v147, v170
	v_add_u32_e32 v2, v177, v2
; __device__ __forceinline__ void p0_job(const Params& p, char* smem, int job) {
;     ...
;       h1s[tg * 64 + j] = sinf(fr * a);
;       __syncthreads();
;       float a2 = b2;
;       for (int i = 0; i < 64; ++i) a2 += h1s[tg * 64 + i] * w2[i * 64 + j];
.LBB0_56:
	s_andn2_saveexec_b64 s[0:1], s[26:27]
	v_mul_f32_e64 v2, |v0|, s56
	v_rndne_f32_e32 v4, v2
	v_cvt_i32_f32_e32 v2, v4
	v_fma_f32 v3, v4, s57, |v0|
	v_fmac_f32_e32 v3, 0xb3a22168, v4
	v_fmac_f32_e32 v3, 0xa7c234c4, v4
	s_or_b64 exec, exec, s[0:1]
	v_mul_f32_e32 v4, v3, v3
	v_fmamk_f32 v147, v4, 0xb94c1982, v150
	v_fmaak_f32 v147, v4, v147, 0xbe2aaa9d
	v_mul_f32_e32 v147, v4, v147
	v_fmac_f32_e32 v3, v3, v147
	v_fmamk_f32 v147, v4, 0x37d75334, v151
	v_fmaak_f32 v147, v4, v147, 0x3d2aabf7
	v_fmaak_f32 v147, v4, v147, 0xbf000004
	v_fma_f32 v4, v4, v147, 1.0
	v_and_b32_e32 v147, 1, v2
	v_lshlrev_b32_e32 v2, 30, v2
	v_cmp_eq_u32_e32 vcc, 0, v147
	v_and_b32_e32 v2, 0x80000000, v2
	v_xor_b32_e32 v1, v1, v0
	v_cndmask_b32_e32 v3, v4, v3, vcc
	v_xor_b32_e32 v1, v1, v2
	v_xor_b32_e32 v1, v1, v3
	v_cmp_class_f32_e64 vcc, v0, s59
	s_nop 1
	v_cndmask_b32_e32 v0, v158, v1, vcc
	ds_write_b32 v167, v0 offset:576
	s_waitcnt lgkmcnt(0)
	s_barrier
	ds_read_b128 v[0:3], v168 offset:576
	ds_read_b128 v[174:177], v168 offset:592
	ds_read_b128 v[178:181], v168 offset:608
	ds_read_b128 v[182:185], v168 offset:624
	global_load_dword v186, v[46:47], off
	global_load_dword v187, v[48:49], off
	global_load_dword v188, v[46:47], off offset:256
	global_load_dword v189, v[46:47], off offset:512
	global_load_dword v190, v[46:47], off offset:768
	global_load_dword v191, v[46:47], off offset:1024
	global_load_dword v192, v[46:47], off offset:1280
	global_load_dword v193, v[46:47], off offset:1536
	global_load_dword v194, v[46:47], off offset:1792
	global_load_dword v195, v[46:47], off offset:2048
	global_load_dword v196, v[46:47], off offset:2304
	global_load_dword v197, v[46:47], off offset:2560
	global_load_dword v198, v[46:47], off offset:2816
	global_load_dword v199, v[46:47], off offset:3072
	global_load_dword v200, v[46:47], off offset:3328
	global_load_dword v201, v[46:47], off offset:3584
	global_load_dword v202, v[46:47], off offset:3840
	global_load_dword v204, v[50:51], off
	global_load_dword v205, v[56:57], off
	global_load_dword v206, v[52:53], off
	global_load_dword v207, v[54:55], off
	global_load_dword v208, v[58:59], off
	global_load_dword v209, v[64:65], off
	global_load_dword v210, v[60:61], off
	global_load_dword v211, v[62:63], off
	global_load_dword v212, v[66:67], off
	global_load_dword v213, v[72:73], off
	global_load_dword v214, v[68:69], off
	global_load_dword v215, v[70:71], off
	global_load_dword v216, v[74:75], off
	global_load_dword v217, v[80:81], off
	global_load_dword v218, v[76:77], off
	global_load_dword v219, v[78:79], off
	global_load_dword v220, v[84:85], off
	global_load_dword v221, v[90:91], off
	global_load_dword v222, v[86:87], off
	global_load_dword v223, v[88:89], off
	global_load_dword v224, v[92:93], off
	global_load_dword v225, v[98:99], off
	global_load_dword v226, v[94:95], off
	global_load_dword v227, v[96:97], off
	global_load_dword v203, v[100:101], off
	global_load_dword v228, v[106:107], off
	global_load_dword v229, v[102:103], off
	global_load_dword v230, v[104:105], off
	global_load_dword v231, v[108:109], off
	global_load_dword v232, v[114:115], off
	global_load_dword v233, v[110:111], off
	global_load_dword v234, v[112:113], off
	global_load_dword v235, v[116:117], off
	global_load_dword v240, v[122:123], off
	global_load_dword v241, v[118:119], off
	global_load_dword v242, v[120:121], off
	global_load_dword v243, v[124:125], off
	global_load_dword v244, v[126:127], off
	global_load_dword v245, v[128:129], off
	global_load_dword v246, v[130:131], off
	global_load_dword v247, v[132:133], off
	global_load_dword v248, v[134:135], off
	global_load_dword v249, v[136:137], off
	global_load_dword v250, v[138:139], off
	global_load_dword v251, v[140:141], off
	global_load_dword v252, v[142:143], off
	global_load_dword v253, v[144:145], off
	s_waitcnt vmcnt(0)
	s_waitcnt lgkmcnt(3)
	v_fma_f32 v4, v0, v186, v163
	v_fmac_f32_e32 v4, v1, v188
	v_fmac_f32_e32 v4, v2, v189
	v_fmac_f32_e32 v4, v3, v190
	s_waitcnt lgkmcnt(2)
	v_fmac_f32_e32 v4, v174, v191
	v_fmac_f32_e32 v4, v175, v192
	v_fmac_f32_e32 v4, v176, v193
	v_fmac_f32_e32 v4, v177, v194
	s_waitcnt lgkmcnt(1)
	v_fmac_f32_e32 v4, v178, v195
	v_fmac_f32_e32 v4, v179, v196
	v_fmac_f32_e32 v4, v180, v197
	v_fmac_f32_e32 v4, v181, v198
	s_waitcnt lgkmcnt(0)
	v_fmac_f32_e32 v4, v182, v199
	v_fmac_f32_e32 v4, v183, v200
	v_fmac_f32_e32 v4, v184, v201
	v_fmac_f32_e32 v4, v185, v202
	ds_read_b128 v[0:3], v168 offset:640
	s_waitcnt lgkmcnt(0)
	v_fmac_f32_e32 v4, v0, v187
	v_fmac_f32_e32 v4, v1, v204
	v_fmac_f32_e32 v4, v2, v206
	v_fmac_f32_e32 v4, v3, v207
	ds_read_b128 v[0:3], v168 offset:656
	s_waitcnt lgkmcnt(0)
	v_fmac_f32_e32 v4, v0, v205
	v_fmac_f32_e32 v4, v1, v208
	v_fmac_f32_e32 v4, v2, v210
	v_fmac_f32_e32 v4, v3, v211
	ds_read_b128 v[0:3], v168 offset:672
	s_waitcnt lgkmcnt(0)
	v_fmac_f32_e32 v4, v0, v209
	v_fmac_f32_e32 v4, v1, v212
	v_fmac_f32_e32 v4, v2, v214
	v_fmac_f32_e32 v4, v3, v215
	ds_read_b128 v[0:3], v168 offset:688
	s_waitcnt lgkmcnt(0)
	v_fmac_f32_e32 v4, v0, v213
	v_fmac_f32_e32 v4, v1, v216
	v_fmac_f32_e32 v4, v2, v218
	v_fmac_f32_e32 v4, v3, v219
	ds_read_b128 v[0:3], v168 offset:704
	s_waitcnt lgkmcnt(0)
	v_fmac_f32_e32 v4, v0, v217
	v_fmac_f32_e32 v4, v1, v220
	v_fmac_f32_e32 v4, v2, v222
	v_fmac_f32_e32 v4, v3, v223
	ds_read_b128 v[0:3], v168 offset:720
	s_waitcnt lgkmcnt(0)
	v_fmac_f32_e32 v4, v0, v221
	v_fmac_f32_e32 v4, v1, v224
	v_fmac_f32_e32 v4, v2, v226
	v_fmac_f32_e32 v4, v3, v227
	ds_read_b128 v[0:3], v168 offset:736
	s_waitcnt lgkmcnt(0)
	v_fmac_f32_e32 v4, v0, v225
	v_fmac_f32_e32 v4, v1, v203
	v_fmac_f32_e32 v4, v2, v229
	v_fmac_f32_e32 v4, v3, v230
	ds_read_b128 v[0:3], v168 offset:752
	s_waitcnt lgkmcnt(0)
	v_fmac_f32_e32 v4, v0, v228
	v_fmac_f32_e32 v4, v1, v231
	v_fmac_f32_e32 v4, v2, v233
	v_fmac_f32_e32 v4, v3, v234
	ds_read_b128 v[0:3], v168 offset:768
	s_waitcnt lgkmcnt(0)
	v_fmac_f32_e32 v4, v0, v232
	v_fmac_f32_e32 v4, v1, v235
	v_fmac_f32_e32 v4, v2, v241
	v_fmac_f32_e32 v4, v3, v242
	ds_read_b128 v[0:3], v168 offset:784
	s_waitcnt lgkmcnt(0)
	v_fmac_f32_e32 v4, v0, v240
	v_fmac_f32_e32 v4, v1, v243
	v_pk_mul_f32 v[0:1], v[2:3], v[244:245]
	s_nop 0
	v_add_f32_e32 v0, v4, v0
	v_add_f32_e32 v4, v0, v1
	ds_read_b128 v[0:3], v168 offset:800
	s_waitcnt lgkmcnt(0)
	v_pk_mul_f32 v[0:1], v[0:1], v[246:247]
	s_nop 0
	v_add_f32_e32 v0, v4, v0
	v_add_f32_e32 v4, v0, v1
	v_pk_mul_f32 v[0:1], v[2:3], v[248:249]
	s_nop 0
	v_add_f32_e32 v0, v4, v0
	v_add_f32_e32 v4, v0, v1
	ds_read_b128 v[0:3], v168 offset:816
	s_waitcnt lgkmcnt(0)
	v_pk_mul_f32 v[0:1], v[0:1], v[250:251]
	s_nop 0
	v_add_f32_e32 v0, v4, v0
	v_add_f32_e32 v4, v0, v1
	v_pk_mul_f32 v[0:1], v[2:3], v[252:253]
	s_nop 0
	v_add_f32_e32 v0, v4, v0
	v_add_f32_e32 v0, v0, v1
	v_mul_f32_e32 v0, v164, v0
	v_and_b32_e32 v1, 0x7fffffff, v0
	v_cmp_nlt_f32_e64 s[0:1], |v0|, s47
	s_and_saveexec_b64 s[10:11], s[0:1]
	s_xor_b64 s[26:27], exec, s[10:11]
	s_cbranch_execz .LBB0_60
; __device__ __forceinline__ void p0_job(const Params& p, char* smem, int job) {
;     ...
;       ((float*)(ws + OFF_HYH))[((size_t)l * 8448 + (Lsel ? 8192 : 0) + t) * 64 + j] = sinf(fr * a2);
	v_lshrrev_b32_e32 v2, 23, v1
	v_add_u32_e32 v2, 0xffffff88, v2
	v_cmp_lt_u32_e32 vcc, 63, v2
	s_nop 1
	v_cndmask_b32_e32 v3, 0, v156, vcc
	v_add_u32_e32 v2, v3, v2
	v_cmp_lt_u32_e64 s[0:1], 31, v2
	s_nop 1
	v_cndmask_b32_e64 v3, 0, v157, s[0:1]
	v_add_u32_e32 v2, v3, v2
	v_cmp_lt_u32_e64 s[12:13], 31, v2
	s_nop 1
	v_cndmask_b32_e64 v3, 0, v157, s[12:13]
	v_add_u32_e32 v147, v3, v2
	v_and_b32_e32 v2, 0x7fffff, v1
	v_or_b32_e32 v173, 0x800000, v2
	v_mad_u64_u32 v[2:3], s[10:11], v173, s48, 0
	v_mov_b32_e32 v4, v3
	v_mad_u64_u32 v[170:171], s[10:11], v173, s49, v[4:5]
	v_mov_b32_e32 v4, v171
	v_mad_u64_u32 v[174:175], s[10:11], v173, s50, v[4:5]
	v_mov_b32_e32 v4, v175
	v_mad_u64_u32 v[176:177], s[10:11], v173, s51, v[4:5]
	v_mov_b32_e32 v4, v177
	v_mad_u64_u32 v[178:179], s[10:11], v173, s52, v[4:5]
	v_mov_b32_e32 v4, v179
	v_mad_u64_u32 v[180:181], s[10:11], v173, s53, v[4:5]
	v_mov_b32_e32 v4, v181
	v_mad_u64_u32 v[182:183], s[10:11], v173, s54, v[4:5]
	v_cndmask_b32_e32 v3, v180, v176, vcc
	v_cndmask_b32_e32 v4, v182, v178, vcc
	v_cndmask_b32_e32 v173, v183, v180, vcc
	v_cndmask_b32_e64 v171, v4, v3, s[0:1]
	v_cndmask_b32_e64 v4, v173, v4, s[0:1]
	v_cndmask_b32_e32 v173, v178, v174, vcc
	v_cndmask_b32_e64 v3, v3, v173, s[0:1]
	v_sub_u32_e32 v175, 32, v147
	v_cmp_eq_u32_e64 s[14:15], 0, v147
	v_cndmask_b32_e32 v147, v176, v170, vcc
	v_cndmask_b32_e64 v4, v4, v171, s[12:13]
	v_cndmask_b32_e64 v171, v171, v3, s[12:13]
	v_cndmask_b32_e64 v170, v173, v147, s[0:1]
	v_alignbit_b32 v177, v4, v171, v175
	v_cndmask_b32_e64 v3, v3, v170, s[12:13]
	v_cndmask_b32_e64 v4, v177, v4, s[14:15]
	v_alignbit_b32 v173, v171, v3, v175
	v_cndmask_b32_e32 v2, v174, v2, vcc
	v_cndmask_b32_e64 v171, v173, v171, s[14:15]
	v_bfe_u32 v177, v4, 29, 1
	v_cndmask_b32_e64 v2, v147, v2, s[0:1]
	v_alignbit_b32 v173, v4, v171, 30
	v_sub_u32_e32 v178, 0, v177
	v_cndmask_b32_e64 v2, v170, v2, s[12:13]
	v_xor_b32_e32 v173, v173, v178
	v_alignbit_b32 v147, v3, v2, v175
	v_cndmask_b32_e64 v3, v147, v3, s[14:15]
	v_ffbh_u32_e32 v170, v173
	v_alignbit_b32 v147, v171, v3, 30
	v_min_u32_e32 v170, 32, v170
	v_alignbit_b32 v2, v3, v2, 30
	v_xor_b32_e32 v147, v147, v178
	v_sub_u32_e32 v171, 31, v170
	v_xor_b32_e32 v2, v2, v178
	v_alignbit_b32 v173, v173, v147, v171
	v_alignbit_b32 v2, v147, v2, v171
	v_alignbit_b32 v3, v173, v2, 9
	v_ffbh_u32_e32 v147, v3
	v_min_u32_e32 v147, 32, v147
	v_lshrrev_b32_e32 v176, 29, v4
	v_not_b32_e32 v171, v147
	v_alignbit_b32 v2, v3, v2, v171
	v_lshlrev_b32_e32 v3, 31, v176
	v_or_b32_e32 v171, 0x33000000, v3
	v_add_lshl_u32 v147, v147, v170, 23
	v_lshrrev_b32_e32 v2, 9, v2
	v_sub_u32_e32 v147, v171, v147
	v_or_b32_e32 v3, 0.5, v3
	v_lshlrev_b32_e32 v170, 23, v170
	v_or_b32_e32 v2, v147, v2
	v_lshrrev_b32_e32 v147, 9, v173
	v_sub_u32_e32 v3, v3, v170
	v_or_b32_e32 v3, v147, v3
	v_mul_f32_e32 v147, 0x3fc90fda, v3
	v_fma_f32 v170, v3, s55, -v147
	v_fmac_f32_e32 v170, 0x33a22168, v3
	v_fmac_f32_e32 v170, 0x3fc90fda, v2
	v_lshrrev_b32_e32 v2, 30, v4
	v_add_f32_e32 v3, v147, v170
	v_add_u32_e32 v2, v177, v2
